# gemm_in sub-step (a): fragment reads ordered by first use (A0[0], B0[0] first) with one counted lgkmcnt per MFMA of the first group
# speedup vs baseline: 1.0071x; 1.0071x over previous
.Lgin_loop:
	s_waitcnt vmcnt(4)
	s_barrier
	ds_read_b128 v[230:233], v175 offset:0
	ds_read_b128 v[182:185], v176 offset:16384
	ds_read_b128 v[234:237], v175 offset:2048
	ds_read_b128 v[238:241], v175 offset:4096
	ds_read_b128 v[242:245], v175 offset:6144
	ds_read_b128 v[136:139], v177 offset:0
	ds_read_b128 v[140:143], v177 offset:2048
	ds_read_b128 v[144:147], v177 offset:4096
	ds_read_b128 v[148:151], v177 offset:6144
	ds_read_b128 v[186:189], v176 offset:18432
	ds_read_b128 v[190:193], v176 offset:20480
	ds_read_b128 v[194:197], v176 offset:22528
	s_add_u32 m0, s11, 0xc000
	s_waitcnt lgkmcnt(10)
	v_mfma_f32_16x16x32_f16 v[124:127], v[230:233], v[182:185], v[124:127]
	s_waitcnt lgkmcnt(9)
	v_mfma_f32_16x16x32_f16 v[92:95], v[234:237], v[182:185], v[92:95]
	s_waitcnt lgkmcnt(8)
	v_mfma_f32_16x16x32_f16 v[60:63], v[238:241], v[182:185], v[60:63]
	s_waitcnt lgkmcnt(7)
	v_mfma_f32_16x16x32_f16 v[28:31], v[242:245], v[182:185], v[28:31]
	global_load_lds_dwordx4 v128, s[6:7]
	s_barrier
	ds_read_b128 v[198:201], v178 offset:16384
	ds_read_b128 v[202:205], v178 offset:18432
	ds_read_b128 v[222:225], v178 offset:20480
	ds_read_b128 v[226:229], v178 offset:22528
	s_add_u32 m0, s11, 0xd000
	s_waitcnt lgkmcnt(6)
	v_mfma_f32_16x16x32_f16 v[120:123], v[230:233], v[186:189], v[120:123]
	v_mfma_f32_16x16x32_f16 v[88:91], v[234:237], v[186:189], v[88:91]
	v_mfma_f32_16x16x32_f16 v[56:59], v[238:241], v[186:189], v[56:59]
	v_mfma_f32_16x16x32_f16 v[24:27], v[242:245], v[186:189], v[24:27]
	global_load_lds_dwordx4 v129, s[6:7]
	s_add_u32 m0, s11, 0xe000
	s_waitcnt lgkmcnt(5)
	v_mfma_f32_16x16x32_f16 v[116:119], v[230:233], v[190:193], v[116:119]
	v_mfma_f32_16x16x32_f16 v[84:87], v[234:237], v[190:193], v[84:87]
	v_mfma_f32_16x16x32_f16 v[52:55], v[238:241], v[190:193], v[52:55]
	v_mfma_f32_16x16x32_f16 v[20:23], v[242:245], v[190:193], v[20:23]
	global_load_lds_dwordx4 v132, s[6:7]
	s_add_u32 m0, s11, 0xf000
	s_waitcnt lgkmcnt(4)
	v_mfma_f32_16x16x32_f16 v[112:115], v[230:233], v[194:197], v[112:115]
	v_mfma_f32_16x16x32_f16 v[80:83], v[234:237], v[194:197], v[80:83]
	v_mfma_f32_16x16x32_f16 v[48:51], v[238:241], v[194:197], v[48:51]
	v_mfma_f32_16x16x32_f16 v[16:19], v[242:245], v[194:197], v[16:19]
	global_load_lds_dwordx4 v133, s[6:7]
	s_add_u32 m0, s11, 0x0
	s_waitcnt lgkmcnt(3)
	v_mfma_f32_16x16x32_f16 v[124:127], v[136:139], v[198:201], v[124:127]
	v_mfma_f32_16x16x32_f16 v[92:95], v[140:143], v[198:201], v[92:95]
	v_mfma_f32_16x16x32_f16 v[60:63], v[144:147], v[198:201], v[60:63]
	v_mfma_f32_16x16x32_f16 v[28:31], v[148:151], v[198:201], v[28:31]
	global_load_lds_dwordx4 v128, s[4:5]
	s_add_u32 m0, s11, 0x1000
	s_waitcnt lgkmcnt(2)
	v_mfma_f32_16x16x32_f16 v[120:123], v[136:139], v[202:205], v[120:123]
	v_mfma_f32_16x16x32_f16 v[88:91], v[140:143], v[202:205], v[88:91]
	v_mfma_f32_16x16x32_f16 v[56:59], v[144:147], v[202:205], v[56:59]
	v_mfma_f32_16x16x32_f16 v[24:27], v[148:151], v[202:205], v[24:27]
	global_load_lds_dwordx4 v129, s[4:5]
	s_add_u32 m0, s11, 0x2000
	s_waitcnt lgkmcnt(1)
	v_mfma_f32_16x16x32_f16 v[116:119], v[136:139], v[222:225], v[116:119]
	v_mfma_f32_16x16x32_f16 v[84:87], v[140:143], v[222:225], v[84:87]
	v_mfma_f32_16x16x32_f16 v[52:55], v[144:147], v[222:225], v[52:55]
	v_mfma_f32_16x16x32_f16 v[20:23], v[148:151], v[222:225], v[20:23]
	global_load_lds_dwordx4 v130, s[4:5]
	s_add_u32 m0, s11, 0x3000
	s_waitcnt lgkmcnt(0)
	v_mfma_f32_16x16x32_f16 v[112:115], v[136:139], v[226:229], v[112:115]
	v_mfma_f32_16x16x32_f16 v[80:83], v[140:143], v[226:229], v[80:83]
	v_mfma_f32_16x16x32_f16 v[48:51], v[144:147], v[226:229], v[48:51]
	v_mfma_f32_16x16x32_f16 v[16:19], v[148:151], v[226:229], v[16:19]
	global_load_lds_dwordx4 v131, s[4:5]
	s_add_u32 s6, s6, 128
	s_addc_u32 s7, s7, 0
	s_add_u32 s4, s4, 128
	s_addc_u32 s5, s5, 0
	s_waitcnt vmcnt(8)
	s_barrier
	ds_read_b128 v[182:185], v176 offset:32768
	ds_read_b128 v[186:189], v176 offset:34816
	ds_read_b128 v[190:193], v176 offset:36864
	ds_read_b128 v[194:197], v176 offset:38912
	ds_read_b128 v[198:201], v178 offset:32768
	ds_read_b128 v[202:205], v178 offset:34816
	ds_read_b128 v[222:225], v178 offset:36864
	ds_read_b128 v[226:229], v178 offset:38912
	s_add_u32 m0, s11, 0x4000
	s_waitcnt lgkmcnt(7)
	v_mfma_f32_16x16x32_f16 v[108:111], v[230:233], v[182:185], v[108:111]
	v_mfma_f32_16x16x32_f16 v[76:79], v[234:237], v[182:185], v[76:79]
	v_mfma_f32_16x16x32_f16 v[44:47], v[238:241], v[182:185], v[44:47]
	v_mfma_f32_16x16x32_f16 v[12:15], v[242:245], v[182:185], v[12:15]
	global_load_lds_dwordx4 v128, s[18:19]
	s_add_u32 m0, s11, 0x5000
	s_waitcnt lgkmcnt(6)
	v_mfma_f32_16x16x32_f16 v[104:107], v[230:233], v[186:189], v[104:107]
	v_mfma_f32_16x16x32_f16 v[72:75], v[234:237], v[186:189], v[72:75]
	v_mfma_f32_16x16x32_f16 v[40:43], v[238:241], v[186:189], v[40:43]
	v_mfma_f32_16x16x32_f16 v[8:11], v[242:245], v[186:189], v[8:11]
	global_load_lds_dwordx4 v129, s[18:19]
	s_add_u32 m0, s11, 0x6000
	s_waitcnt lgkmcnt(5)
	v_mfma_f32_16x16x32_f16 v[100:103], v[230:233], v[190:193], v[100:103]
	v_mfma_f32_16x16x32_f16 v[68:71], v[234:237], v[190:193], v[68:71]
	v_mfma_f32_16x16x32_f16 v[36:39], v[238:241], v[190:193], v[36:39]
	v_mfma_f32_16x16x32_f16 v[4:7], v[242:245], v[190:193], v[4:7]
	global_load_lds_dwordx4 v132, s[18:19]
	s_add_u32 m0, s11, 0x7000
	s_waitcnt lgkmcnt(4)
	v_mfma_f32_16x16x32_f16 v[96:99], v[230:233], v[194:197], v[96:99]
	v_mfma_f32_16x16x32_f16 v[64:67], v[234:237], v[194:197], v[64:67]
	v_mfma_f32_16x16x32_f16 v[32:35], v[238:241], v[194:197], v[32:35]
	v_mfma_f32_16x16x32_f16 v[0:3], v[242:245], v[194:197], v[0:3]
	global_load_lds_dwordx4 v133, s[18:19]
	s_waitcnt lgkmcnt(3)
	v_mfma_f32_16x16x32_f16 v[108:111], v[136:139], v[198:201], v[108:111]
	v_mfma_f32_16x16x32_f16 v[76:79], v[140:143], v[198:201], v[76:79]
	v_mfma_f32_16x16x32_f16 v[44:47], v[144:147], v[198:201], v[44:47]
	v_mfma_f32_16x16x32_f16 v[12:15], v[148:151], v[198:201], v[12:15]
	s_waitcnt lgkmcnt(2)
	v_mfma_f32_16x16x32_f16 v[104:107], v[136:139], v[202:205], v[104:107]
	v_mfma_f32_16x16x32_f16 v[72:75], v[140:143], v[202:205], v[72:75]
	v_mfma_f32_16x16x32_f16 v[40:43], v[144:147], v[202:205], v[40:43]
	v_mfma_f32_16x16x32_f16 v[8:11], v[148:151], v[202:205], v[8:11]
	s_waitcnt lgkmcnt(1)
	v_mfma_f32_16x16x32_f16 v[100:103], v[136:139], v[222:225], v[100:103]
	v_mfma_f32_16x16x32_f16 v[68:71], v[140:143], v[222:225], v[68:71]
	v_mfma_f32_16x16x32_f16 v[36:39], v[144:147], v[222:225], v[36:39]
	v_mfma_f32_16x16x32_f16 v[4:7], v[148:151], v[222:225], v[4:7]
	s_waitcnt lgkmcnt(0)
	v_mfma_f32_16x16x32_f16 v[96:99], v[136:139], v[226:229], v[96:99]
	v_mfma_f32_16x16x32_f16 v[64:67], v[140:143], v[226:229], v[64:67]
	v_mfma_f32_16x16x32_f16 v[32:35], v[144:147], v[226:229], v[32:35]
	v_mfma_f32_16x16x32_f16 v[0:3], v[148:151], v[226:229], v[0:3]
	s_add_u32 s18, s18, 128
	s_addc_u32 s19, s19, 0
	s_waitcnt vmcnt(4)
	s_barrier
	ds_read_b128 v[230:233], v175 offset:0
	ds_read_b128 v[182:185], v176 offset:49152
	ds_read_b128 v[234:237], v175 offset:2048
	ds_read_b128 v[238:241], v175 offset:4096
	ds_read_b128 v[242:245], v175 offset:6144
	ds_read_b128 v[136:139], v177 offset:0
	ds_read_b128 v[140:143], v177 offset:2048
	ds_read_b128 v[144:147], v177 offset:4096
	ds_read_b128 v[148:151], v177 offset:6144
	ds_read_b128 v[186:189], v176 offset:51200
	ds_read_b128 v[190:193], v176 offset:53248
	ds_read_b128 v[194:197], v176 offset:55296
	s_add_u32 m0, s11, 0x8000
	s_waitcnt lgkmcnt(10)
	v_mfma_f32_16x16x32_f16 v[124:127], v[230:233], v[182:185], v[124:127]
	s_waitcnt lgkmcnt(9)
	v_mfma_f32_16x16x32_f16 v[92:95], v[234:237], v[182:185], v[92:95]
	s_waitcnt lgkmcnt(8)
	v_mfma_f32_16x16x32_f16 v[60:63], v[238:241], v[182:185], v[60:63]
	s_waitcnt lgkmcnt(7)
	v_mfma_f32_16x16x32_f16 v[28:31], v[242:245], v[182:185], v[28:31]
	global_load_lds_dwordx4 v128, s[6:7]
	s_barrier
	ds_read_b128 v[198:201], v178 offset:49152
	ds_read_b128 v[202:205], v178 offset:51200
	ds_read_b128 v[222:225], v178 offset:53248
	ds_read_b128 v[226:229], v178 offset:55296
	s_add_u32 m0, s11, 0x9000
	s_waitcnt lgkmcnt(6)
	v_mfma_f32_16x16x32_f16 v[120:123], v[230:233], v[186:189], v[120:123]
	v_mfma_f32_16x16x32_f16 v[88:91], v[234:237], v[186:189], v[88:91]
	v_mfma_f32_16x16x32_f16 v[56:59], v[238:241], v[186:189], v[56:59]
	v_mfma_f32_16x16x32_f16 v[24:27], v[242:245], v[186:189], v[24:27]
	global_load_lds_dwordx4 v129, s[6:7]
	s_add_u32 m0, s11, 0xa000
	s_waitcnt lgkmcnt(5)
	v_mfma_f32_16x16x32_f16 v[116:119], v[230:233], v[190:193], v[116:119]
	v_mfma_f32_16x16x32_f16 v[84:87], v[234:237], v[190:193], v[84:87]
	v_mfma_f32_16x16x32_f16 v[52:55], v[238:241], v[190:193], v[52:55]
	v_mfma_f32_16x16x32_f16 v[20:23], v[242:245], v[190:193], v[20:23]
	global_load_lds_dwordx4 v132, s[6:7]
	s_add_u32 m0, s11, 0xb000
	s_waitcnt lgkmcnt(4)
	v_mfma_f32_16x16x32_f16 v[112:115], v[230:233], v[194:197], v[112:115]
	v_mfma_f32_16x16x32_f16 v[80:83], v[234:237], v[194:197], v[80:83]
	v_mfma_f32_16x16x32_f16 v[48:51], v[238:241], v[194:197], v[48:51]
	v_mfma_f32_16x16x32_f16 v[16:19], v[242:245], v[194:197], v[16:19]
	global_load_lds_dwordx4 v133, s[6:7]
	s_add_u32 m0, s11, 0x0
	s_waitcnt lgkmcnt(3)
	v_mfma_f32_16x16x32_f16 v[124:127], v[136:139], v[198:201], v[124:127]
	v_mfma_f32_16x16x32_f16 v[92:95], v[140:143], v[198:201], v[92:95]
	v_mfma_f32_16x16x32_f16 v[60:63], v[144:147], v[198:201], v[60:63]
	v_mfma_f32_16x16x32_f16 v[28:31], v[148:151], v[198:201], v[28:31]
	global_load_lds_dwordx4 v128, s[4:5]
	s_add_u32 m0, s11, 0x1000
	s_waitcnt lgkmcnt(2)
	v_mfma_f32_16x16x32_f16 v[120:123], v[136:139], v[202:205], v[120:123]
	v_mfma_f32_16x16x32_f16 v[88:91], v[140:143], v[202:205], v[88:91]
	v_mfma_f32_16x16x32_f16 v[56:59], v[144:147], v[202:205], v[56:59]
	v_mfma_f32_16x16x32_f16 v[24:27], v[148:151], v[202:205], v[24:27]
	global_load_lds_dwordx4 v129, s[4:5]
	s_add_u32 m0, s11, 0x2000
	s_waitcnt lgkmcnt(1)
	v_mfma_f32_16x16x32_f16 v[116:119], v[136:139], v[222:225], v[116:119]
	v_mfma_f32_16x16x32_f16 v[84:87], v[140:143], v[222:225], v[84:87]
	v_mfma_f32_16x16x32_f16 v[52:55], v[144:147], v[222:225], v[52:55]
	v_mfma_f32_16x16x32_f16 v[20:23], v[148:151], v[222:225], v[20:23]
	global_load_lds_dwordx4 v130, s[4:5]
	s_add_u32 m0, s11, 0x3000
	s_waitcnt lgkmcnt(0)
	v_mfma_f32_16x16x32_f16 v[112:115], v[136:139], v[226:229], v[112:115]
	v_mfma_f32_16x16x32_f16 v[80:83], v[140:143], v[226:229], v[80:83]
	v_mfma_f32_16x16x32_f16 v[48:51], v[144:147], v[226:229], v[48:51]
	v_mfma_f32_16x16x32_f16 v[16:19], v[148:151], v[226:229], v[16:19]
	global_load_lds_dwordx4 v131, s[4:5]
	s_add_u32 s6, s6, 128
	s_addc_u32 s7, s7, 0
	s_add_u32 s4, s4, 128
	s_addc_u32 s5, s5, 0
	s_waitcnt vmcnt(8)
	s_barrier
	ds_read_b128 v[182:185], v176 offset:16384
	ds_read_b128 v[186:189], v176 offset:18432
	ds_read_b128 v[190:193], v176 offset:20480
	ds_read_b128 v[194:197], v176 offset:22528
	ds_read_b128 v[198:201], v178 offset:16384
	ds_read_b128 v[202:205], v178 offset:18432
	ds_read_b128 v[222:225], v178 offset:20480
	ds_read_b128 v[226:229], v178 offset:22528
	s_add_u32 m0, s11, 0xc000
	s_waitcnt lgkmcnt(7)
	v_mfma_f32_16x16x32_f16 v[108:111], v[230:233], v[182:185], v[108:111]
	v_mfma_f32_16x16x32_f16 v[76:79], v[234:237], v[182:185], v[76:79]
	v_mfma_f32_16x16x32_f16 v[44:47], v[238:241], v[182:185], v[44:47]
	v_mfma_f32_16x16x32_f16 v[12:15], v[242:245], v[182:185], v[12:15]
	global_load_lds_dwordx4 v128, s[18:19]
	s_add_u32 m0, s11, 0xd000
	s_waitcnt lgkmcnt(6)
	v_mfma_f32_16x16x32_f16 v[104:107], v[230:233], v[186:189], v[104:107]
	v_mfma_f32_16x16x32_f16 v[72:75], v[234:237], v[186:189], v[72:75]
	v_mfma_f32_16x16x32_f16 v[40:43], v[238:241], v[186:189], v[40:43]
	v_mfma_f32_16x16x32_f16 v[8:11], v[242:245], v[186:189], v[8:11]
	global_load_lds_dwordx4 v129, s[18:19]
	s_add_u32 m0, s11, 0xe000
	s_waitcnt lgkmcnt(5)
	v_mfma_f32_16x16x32_f16 v[100:103], v[230:233], v[190:193], v[100:103]
	v_mfma_f32_16x16x32_f16 v[68:71], v[234:237], v[190:193], v[68:71]
	v_mfma_f32_16x16x32_f16 v[36:39], v[238:241], v[190:193], v[36:39]
	v_mfma_f32_16x16x32_f16 v[4:7], v[242:245], v[190:193], v[4:7]
	global_load_lds_dwordx4 v132, s[18:19]
	s_add_u32 m0, s11, 0xf000
	s_waitcnt lgkmcnt(4)
	v_mfma_f32_16x16x32_f16 v[96:99], v[230:233], v[194:197], v[96:99]
	v_mfma_f32_16x16x32_f16 v[64:67], v[234:237], v[194:197], v[64:67]
	v_mfma_f32_16x16x32_f16 v[32:35], v[238:241], v[194:197], v[32:35]
	v_mfma_f32_16x16x32_f16 v[0:3], v[242:245], v[194:197], v[0:3]
	global_load_lds_dwordx4 v133, s[18:19]
	s_waitcnt lgkmcnt(3)
	v_mfma_f32_16x16x32_f16 v[108:111], v[136:139], v[198:201], v[108:111]
	v_mfma_f32_16x16x32_f16 v[76:79], v[140:143], v[198:201], v[76:79]
	v_mfma_f32_16x16x32_f16 v[44:47], v[144:147], v[198:201], v[44:47]
	v_mfma_f32_16x16x32_f16 v[12:15], v[148:151], v[198:201], v[12:15]
	s_waitcnt lgkmcnt(2)
	v_mfma_f32_16x16x32_f16 v[104:107], v[136:139], v[202:205], v[104:107]
	v_mfma_f32_16x16x32_f16 v[72:75], v[140:143], v[202:205], v[72:75]
	v_mfma_f32_16x16x32_f16 v[40:43], v[144:147], v[202:205], v[40:43]
	v_mfma_f32_16x16x32_f16 v[8:11], v[148:151], v[202:205], v[8:11]
	s_waitcnt lgkmcnt(1)
	v_mfma_f32_16x16x32_f16 v[100:103], v[136:139], v[222:225], v[100:103]
	v_mfma_f32_16x16x32_f16 v[68:71], v[140:143], v[222:225], v[68:71]
	v_mfma_f32_16x16x32_f16 v[36:39], v[144:147], v[222:225], v[36:39]
	v_mfma_f32_16x16x32_f16 v[4:7], v[148:151], v[222:225], v[4:7]
	s_waitcnt lgkmcnt(0)
	v_mfma_f32_16x16x32_f16 v[96:99], v[136:139], v[226:229], v[96:99]
	v_mfma_f32_16x16x32_f16 v[64:67], v[140:143], v[226:229], v[64:67]
	v_mfma_f32_16x16x32_f16 v[32:35], v[144:147], v[226:229], v[32:35]
	v_mfma_f32_16x16x32_f16 v[0:3], v[148:151], v[226:229], v[0:3]
	s_add_u32 s18, s18, 128
	s_addc_u32 s19, s19, 0
	s_waitcnt vmcnt(4)
	s_barrier
	ds_read_b128 v[230:233], v175 offset:0
	ds_read_b128 v[182:185], v176 offset:32768
	ds_read_b128 v[234:237], v175 offset:2048
	ds_read_b128 v[238:241], v175 offset:4096
	ds_read_b128 v[242:245], v175 offset:6144
	ds_read_b128 v[136:139], v177 offset:0
	ds_read_b128 v[140:143], v177 offset:2048
	ds_read_b128 v[144:147], v177 offset:4096
	ds_read_b128 v[148:151], v177 offset:6144
	ds_read_b128 v[186:189], v176 offset:34816
	ds_read_b128 v[190:193], v176 offset:36864
	ds_read_b128 v[194:197], v176 offset:38912
	s_add_u32 m0, s11, 0x4000
	s_waitcnt lgkmcnt(10)
	v_mfma_f32_16x16x32_f16 v[124:127], v[230:233], v[182:185], v[124:127]
	s_waitcnt lgkmcnt(9)
	v_mfma_f32_16x16x32_f16 v[92:95], v[234:237], v[182:185], v[92:95]
	s_waitcnt lgkmcnt(8)
	v_mfma_f32_16x16x32_f16 v[60:63], v[238:241], v[182:185], v[60:63]
	s_waitcnt lgkmcnt(7)
	v_mfma_f32_16x16x32_f16 v[28:31], v[242:245], v[182:185], v[28:31]
	global_load_lds_dwordx4 v128, s[6:7]
	s_barrier
	ds_read_b128 v[198:201], v178 offset:32768
	ds_read_b128 v[202:205], v178 offset:34816
	ds_read_b128 v[222:225], v178 offset:36864
	ds_read_b128 v[226:229], v178 offset:38912
	s_add_u32 m0, s11, 0x5000
	s_waitcnt lgkmcnt(6)
	v_mfma_f32_16x16x32_f16 v[120:123], v[230:233], v[186:189], v[120:123]
	v_mfma_f32_16x16x32_f16 v[88:91], v[234:237], v[186:189], v[88:91]
	v_mfma_f32_16x16x32_f16 v[56:59], v[238:241], v[186:189], v[56:59]
	v_mfma_f32_16x16x32_f16 v[24:27], v[242:245], v[186:189], v[24:27]
	global_load_lds_dwordx4 v129, s[6:7]
	s_add_u32 m0, s11, 0x6000
	s_waitcnt lgkmcnt(5)
	v_mfma_f32_16x16x32_f16 v[116:119], v[230:233], v[190:193], v[116:119]
	v_mfma_f32_16x16x32_f16 v[84:87], v[234:237], v[190:193], v[84:87]
	v_mfma_f32_16x16x32_f16 v[52:55], v[238:241], v[190:193], v[52:55]
	v_mfma_f32_16x16x32_f16 v[20:23], v[242:245], v[190:193], v[20:23]
	global_load_lds_dwordx4 v132, s[6:7]
	s_add_u32 m0, s11, 0x7000
	s_waitcnt lgkmcnt(4)
	v_mfma_f32_16x16x32_f16 v[112:115], v[230:233], v[194:197], v[112:115]
	v_mfma_f32_16x16x32_f16 v[80:83], v[234:237], v[194:197], v[80:83]
	v_mfma_f32_16x16x32_f16 v[48:51], v[238:241], v[194:197], v[48:51]
	v_mfma_f32_16x16x32_f16 v[16:19], v[242:245], v[194:197], v[16:19]
	global_load_lds_dwordx4 v133, s[6:7]
	s_add_u32 m0, s11, 0x0
	s_waitcnt lgkmcnt(3)
	v_mfma_f32_16x16x32_f16 v[124:127], v[136:139], v[198:201], v[124:127]
	v_mfma_f32_16x16x32_f16 v[92:95], v[140:143], v[198:201], v[92:95]
	v_mfma_f32_16x16x32_f16 v[60:63], v[144:147], v[198:201], v[60:63]
	v_mfma_f32_16x16x32_f16 v[28:31], v[148:151], v[198:201], v[28:31]
	global_load_lds_dwordx4 v128, s[4:5]
	s_add_u32 m0, s11, 0x1000
	s_waitcnt lgkmcnt(2)
	v_mfma_f32_16x16x32_f16 v[120:123], v[136:139], v[202:205], v[120:123]
	v_mfma_f32_16x16x32_f16 v[88:91], v[140:143], v[202:205], v[88:91]
	v_mfma_f32_16x16x32_f16 v[56:59], v[144:147], v[202:205], v[56:59]
	v_mfma_f32_16x16x32_f16 v[24:27], v[148:151], v[202:205], v[24:27]
	global_load_lds_dwordx4 v129, s[4:5]
	s_add_u32 m0, s11, 0x2000
	s_waitcnt lgkmcnt(1)
	v_mfma_f32_16x16x32_f16 v[116:119], v[136:139], v[222:225], v[116:119]
	v_mfma_f32_16x16x32_f16 v[84:87], v[140:143], v[222:225], v[84:87]
	v_mfma_f32_16x16x32_f16 v[52:55], v[144:147], v[222:225], v[52:55]
	v_mfma_f32_16x16x32_f16 v[20:23], v[148:151], v[222:225], v[20:23]
	global_load_lds_dwordx4 v130, s[4:5]
	s_add_u32 m0, s11, 0x3000
	s_waitcnt lgkmcnt(0)
	v_mfma_f32_16x16x32_f16 v[112:115], v[136:139], v[226:229], v[112:115]
	v_mfma_f32_16x16x32_f16 v[80:83], v[140:143], v[226:229], v[80:83]
	v_mfma_f32_16x16x32_f16 v[48:51], v[144:147], v[226:229], v[48:51]
	v_mfma_f32_16x16x32_f16 v[16:19], v[148:151], v[226:229], v[16:19]
	global_load_lds_dwordx4 v131, s[4:5]
	s_add_u32 s6, s6, 128
	s_addc_u32 s7, s7, 0
	s_add_u32 s4, s4, 128
	s_addc_u32 s5, s5, 0
	s_waitcnt vmcnt(8)
	s_barrier
	ds_read_b128 v[182:185], v176 offset:49152
	ds_read_b128 v[186:189], v176 offset:51200
	ds_read_b128 v[190:193], v176 offset:53248
	ds_read_b128 v[194:197], v176 offset:55296
	ds_read_b128 v[198:201], v178 offset:49152
	ds_read_b128 v[202:205], v178 offset:51200
	ds_read_b128 v[222:225], v178 offset:53248
	ds_read_b128 v[226:229], v178 offset:55296
	s_add_u32 m0, s11, 0x8000
	s_waitcnt lgkmcnt(7)
	v_mfma_f32_16x16x32_f16 v[108:111], v[230:233], v[182:185], v[108:111]
	v_mfma_f32_16x16x32_f16 v[76:79], v[234:237], v[182:185], v[76:79]
	v_mfma_f32_16x16x32_f16 v[44:47], v[238:241], v[182:185], v[44:47]
	v_mfma_f32_16x16x32_f16 v[12:15], v[242:245], v[182:185], v[12:15]
	global_load_lds_dwordx4 v128, s[18:19]
	s_add_u32 m0, s11, 0x9000
	s_waitcnt lgkmcnt(6)
	v_mfma_f32_16x16x32_f16 v[104:107], v[230:233], v[186:189], v[104:107]
	v_mfma_f32_16x16x32_f16 v[72:75], v[234:237], v[186:189], v[72:75]
	v_mfma_f32_16x16x32_f16 v[40:43], v[238:241], v[186:189], v[40:43]
	v_mfma_f32_16x16x32_f16 v[8:11], v[242:245], v[186:189], v[8:11]
	global_load_lds_dwordx4 v129, s[18:19]
	s_add_u32 m0, s11, 0xa000
	s_waitcnt lgkmcnt(5)
	v_mfma_f32_16x16x32_f16 v[100:103], v[230:233], v[190:193], v[100:103]
	v_mfma_f32_16x16x32_f16 v[68:71], v[234:237], v[190:193], v[68:71]
	v_mfma_f32_16x16x32_f16 v[36:39], v[238:241], v[190:193], v[36:39]
	v_mfma_f32_16x16x32_f16 v[4:7], v[242:245], v[190:193], v[4:7]
	global_load_lds_dwordx4 v132, s[18:19]
	s_add_u32 m0, s11, 0xb000
	s_waitcnt lgkmcnt(4)
	v_mfma_f32_16x16x32_f16 v[96:99], v[230:233], v[194:197], v[96:99]
	v_mfma_f32_16x16x32_f16 v[64:67], v[234:237], v[194:197], v[64:67]
	v_mfma_f32_16x16x32_f16 v[32:35], v[238:241], v[194:197], v[32:35]
	v_mfma_f32_16x16x32_f16 v[0:3], v[242:245], v[194:197], v[0:3]
	global_load_lds_dwordx4 v133, s[18:19]
	s_waitcnt lgkmcnt(3)
	v_mfma_f32_16x16x32_f16 v[108:111], v[136:139], v[198:201], v[108:111]
	v_mfma_f32_16x16x32_f16 v[76:79], v[140:143], v[198:201], v[76:79]
	v_mfma_f32_16x16x32_f16 v[44:47], v[144:147], v[198:201], v[44:47]
	v_mfma_f32_16x16x32_f16 v[12:15], v[148:151], v[198:201], v[12:15]
	s_waitcnt lgkmcnt(2)
	v_mfma_f32_16x16x32_f16 v[104:107], v[136:139], v[202:205], v[104:107]
	v_mfma_f32_16x16x32_f16 v[72:75], v[140:143], v[202:205], v[72:75]
	v_mfma_f32_16x16x32_f16 v[40:43], v[144:147], v[202:205], v[40:43]
	v_mfma_f32_16x16x32_f16 v[8:11], v[148:151], v[202:205], v[8:11]
	s_waitcnt lgkmcnt(1)
	v_mfma_f32_16x16x32_f16 v[100:103], v[136:139], v[222:225], v[100:103]
	v_mfma_f32_16x16x32_f16 v[68:71], v[140:143], v[222:225], v[68:71]
	v_mfma_f32_16x16x32_f16 v[36:39], v[144:147], v[222:225], v[36:39]
	v_mfma_f32_16x16x32_f16 v[4:7], v[148:151], v[222:225], v[4:7]
	s_waitcnt lgkmcnt(0)
	v_mfma_f32_16x16x32_f16 v[96:99], v[136:139], v[226:229], v[96:99]
	v_mfma_f32_16x16x32_f16 v[64:67], v[140:143], v[226:229], v[64:67]
	v_mfma_f32_16x16x32_f16 v[32:35], v[144:147], v[226:229], v[32:35]
	v_mfma_f32_16x16x32_f16 v[0:3], v[148:151], v[226:229], v[0:3]
	s_add_u32 s18, s18, 128
	s_addc_u32 s19, s19, 0
	s_add_i32 s10, s10, 1
	s_cmp_lt_u32 s10, 10
	s_cbranch_scc1 .Lgin_loop
	s_waitcnt vmcnt(4)
	s_barrier
	ds_read_b128 v[230:233], v175 offset:0
	ds_read_b128 v[182:185], v176 offset:16384
	ds_read_b128 v[234:237], v175 offset:2048
	ds_read_b128 v[238:241], v175 offset:4096
	ds_read_b128 v[242:245], v175 offset:6144
	ds_read_b128 v[136:139], v177 offset:0
	ds_read_b128 v[140:143], v177 offset:2048
	ds_read_b128 v[144:147], v177 offset:4096
	ds_read_b128 v[148:151], v177 offset:6144
	ds_read_b128 v[186:189], v176 offset:18432
	ds_read_b128 v[190:193], v176 offset:20480
	ds_read_b128 v[194:197], v176 offset:22528
	s_add_u32 m0, s11, 0xc000
	s_waitcnt lgkmcnt(10)
	v_mfma_f32_16x16x32_f16 v[124:127], v[230:233], v[182:185], v[124:127]
	s_waitcnt lgkmcnt(9)
	v_mfma_f32_16x16x32_f16 v[92:95], v[234:237], v[182:185], v[92:95]
	s_waitcnt lgkmcnt(8)
	v_mfma_f32_16x16x32_f16 v[60:63], v[238:241], v[182:185], v[60:63]
	s_waitcnt lgkmcnt(7)
	v_mfma_f32_16x16x32_f16 v[28:31], v[242:245], v[182:185], v[28:31]
	global_load_lds_dwordx4 v128, s[6:7]
	s_barrier
	ds_read_b128 v[198:201], v178 offset:16384
	ds_read_b128 v[202:205], v178 offset:18432
	ds_read_b128 v[222:225], v178 offset:20480
	ds_read_b128 v[226:229], v178 offset:22528
	s_add_u32 m0, s11, 0xd000
	s_waitcnt lgkmcnt(6)
	v_mfma_f32_16x16x32_f16 v[120:123], v[230:233], v[186:189], v[120:123]
	v_mfma_f32_16x16x32_f16 v[88:91], v[234:237], v[186:189], v[88:91]
	v_mfma_f32_16x16x32_f16 v[56:59], v[238:241], v[186:189], v[56:59]
	v_mfma_f32_16x16x32_f16 v[24:27], v[242:245], v[186:189], v[24:27]
	global_load_lds_dwordx4 v129, s[6:7]
	s_add_u32 m0, s11, 0xe000
	s_waitcnt lgkmcnt(5)
	v_mfma_f32_16x16x32_f16 v[116:119], v[230:233], v[190:193], v[116:119]
	v_mfma_f32_16x16x32_f16 v[84:87], v[234:237], v[190:193], v[84:87]
	v_mfma_f32_16x16x32_f16 v[52:55], v[238:241], v[190:193], v[52:55]
	v_mfma_f32_16x16x32_f16 v[20:23], v[242:245], v[190:193], v[20:23]
	global_load_lds_dwordx4 v132, s[6:7]
	s_add_u32 m0, s11, 0xf000
	s_waitcnt lgkmcnt(4)
	v_mfma_f32_16x16x32_f16 v[112:115], v[230:233], v[194:197], v[112:115]
	v_mfma_f32_16x16x32_f16 v[80:83], v[234:237], v[194:197], v[80:83]
	v_mfma_f32_16x16x32_f16 v[48:51], v[238:241], v[194:197], v[48:51]
	v_mfma_f32_16x16x32_f16 v[16:19], v[242:245], v[194:197], v[16:19]
	global_load_lds_dwordx4 v133, s[6:7]
	s_add_u32 m0, s11, 0x0
	s_waitcnt lgkmcnt(3)
	v_mfma_f32_16x16x32_f16 v[124:127], v[136:139], v[198:201], v[124:127]
	v_mfma_f32_16x16x32_f16 v[92:95], v[140:143], v[198:201], v[92:95]
	v_mfma_f32_16x16x32_f16 v[60:63], v[144:147], v[198:201], v[60:63]
	v_mfma_f32_16x16x32_f16 v[28:31], v[148:151], v[198:201], v[28:31]
	global_load_lds_dwordx4 v128, s[4:5]
	s_add_u32 m0, s11, 0x1000
	s_waitcnt lgkmcnt(2)
	v_mfma_f32_16x16x32_f16 v[120:123], v[136:139], v[202:205], v[120:123]
	v_mfma_f32_16x16x32_f16 v[88:91], v[140:143], v[202:205], v[88:91]
	v_mfma_f32_16x16x32_f16 v[56:59], v[144:147], v[202:205], v[56:59]
	v_mfma_f32_16x16x32_f16 v[24:27], v[148:151], v[202:205], v[24:27]
	global_load_lds_dwordx4 v129, s[4:5]
	s_add_u32 m0, s11, 0x2000
	s_waitcnt lgkmcnt(1)
	v_mfma_f32_16x16x32_f16 v[116:119], v[136:139], v[222:225], v[116:119]
	v_mfma_f32_16x16x32_f16 v[84:87], v[140:143], v[222:225], v[84:87]
	v_mfma_f32_16x16x32_f16 v[52:55], v[144:147], v[222:225], v[52:55]
	v_mfma_f32_16x16x32_f16 v[20:23], v[148:151], v[222:225], v[20:23]
	global_load_lds_dwordx4 v130, s[4:5]
	s_add_u32 m0, s11, 0x3000
	s_waitcnt lgkmcnt(0)
	v_mfma_f32_16x16x32_f16 v[112:115], v[136:139], v[226:229], v[112:115]
	v_mfma_f32_16x16x32_f16 v[80:83], v[140:143], v[226:229], v[80:83]
	v_mfma_f32_16x16x32_f16 v[48:51], v[144:147], v[226:229], v[48:51]
	v_mfma_f32_16x16x32_f16 v[16:19], v[148:151], v[226:229], v[16:19]
	global_load_lds_dwordx4 v131, s[4:5]
	s_add_u32 s6, s6, 128
	s_addc_u32 s7, s7, 0
	s_add_u32 s4, s4, 128
	s_addc_u32 s5, s5, 0
	s_waitcnt vmcnt(8)
	s_barrier
	ds_read_b128 v[182:185], v176 offset:32768
	ds_read_b128 v[186:189], v176 offset:34816
	ds_read_b128 v[190:193], v176 offset:36864
	ds_read_b128 v[194:197], v176 offset:38912
	ds_read_b128 v[198:201], v178 offset:32768
	ds_read_b128 v[202:205], v178 offset:34816
	ds_read_b128 v[222:225], v178 offset:36864
	ds_read_b128 v[226:229], v178 offset:38912
	s_add_u32 m0, s11, 0x4000
	s_waitcnt lgkmcnt(7)
	v_mfma_f32_16x16x32_f16 v[108:111], v[230:233], v[182:185], v[108:111]
	v_mfma_f32_16x16x32_f16 v[76:79], v[234:237], v[182:185], v[76:79]
	v_mfma_f32_16x16x32_f16 v[44:47], v[238:241], v[182:185], v[44:47]
	v_mfma_f32_16x16x32_f16 v[12:15], v[242:245], v[182:185], v[12:15]
	global_load_lds_dwordx4 v128, s[18:19]
	s_add_u32 m0, s11, 0x5000
	s_waitcnt lgkmcnt(6)
	v_mfma_f32_16x16x32_f16 v[104:107], v[230:233], v[186:189], v[104:107]
	v_mfma_f32_16x16x32_f16 v[72:75], v[234:237], v[186:189], v[72:75]
	v_mfma_f32_16x16x32_f16 v[40:43], v[238:241], v[186:189], v[40:43]
	v_mfma_f32_16x16x32_f16 v[8:11], v[242:245], v[186:189], v[8:11]
	global_load_lds_dwordx4 v129, s[18:19]
	s_add_u32 m0, s11, 0x6000
	s_waitcnt lgkmcnt(5)
	v_mfma_f32_16x16x32_f16 v[100:103], v[230:233], v[190:193], v[100:103]
	v_mfma_f32_16x16x32_f16 v[68:71], v[234:237], v[190:193], v[68:71]
	v_mfma_f32_16x16x32_f16 v[36:39], v[238:241], v[190:193], v[36:39]
	v_mfma_f32_16x16x32_f16 v[4:7], v[242:245], v[190:193], v[4:7]
	global_load_lds_dwordx4 v132, s[18:19]
	s_add_u32 m0, s11, 0x7000
	s_waitcnt lgkmcnt(4)
	v_mfma_f32_16x16x32_f16 v[96:99], v[230:233], v[194:197], v[96:99]
	v_mfma_f32_16x16x32_f16 v[64:67], v[234:237], v[194:197], v[64:67]
	v_mfma_f32_16x16x32_f16 v[32:35], v[238:241], v[194:197], v[32:35]
	v_mfma_f32_16x16x32_f16 v[0:3], v[242:245], v[194:197], v[0:3]
	global_load_lds_dwordx4 v133, s[18:19]
	s_waitcnt lgkmcnt(3)
	v_mfma_f32_16x16x32_f16 v[108:111], v[136:139], v[198:201], v[108:111]
	v_mfma_f32_16x16x32_f16 v[76:79], v[140:143], v[198:201], v[76:79]
	v_mfma_f32_16x16x32_f16 v[44:47], v[144:147], v[198:201], v[44:47]
	v_mfma_f32_16x16x32_f16 v[12:15], v[148:151], v[198:201], v[12:15]
	s_waitcnt lgkmcnt(2)
	v_mfma_f32_16x16x32_f16 v[104:107], v[136:139], v[202:205], v[104:107]
	v_mfma_f32_16x16x32_f16 v[72:75], v[140:143], v[202:205], v[72:75]
	v_mfma_f32_16x16x32_f16 v[40:43], v[144:147], v[202:205], v[40:43]
	v_mfma_f32_16x16x32_f16 v[8:11], v[148:151], v[202:205], v[8:11]
	s_waitcnt lgkmcnt(1)
	v_mfma_f32_16x16x32_f16 v[100:103], v[136:139], v[222:225], v[100:103]
	v_mfma_f32_16x16x32_f16 v[68:71], v[140:143], v[222:225], v[68:71]
	v_mfma_f32_16x16x32_f16 v[36:39], v[144:147], v[222:225], v[36:39]
	v_mfma_f32_16x16x32_f16 v[4:7], v[148:151], v[222:225], v[4:7]
	s_waitcnt lgkmcnt(0)
	v_mfma_f32_16x16x32_f16 v[96:99], v[136:139], v[226:229], v[96:99]
	v_mfma_f32_16x16x32_f16 v[64:67], v[140:143], v[226:229], v[64:67]
	v_mfma_f32_16x16x32_f16 v[32:35], v[144:147], v[226:229], v[32:35]
	v_mfma_f32_16x16x32_f16 v[0:3], v[148:151], v[226:229], v[0:3]
	s_add_u32 s18, s18, 128
	s_addc_u32 s19, s19, 0
	s_waitcnt vmcnt(4)
	s_barrier
	ds_read_b128 v[230:233], v175 offset:0
	ds_read_b128 v[182:185], v176 offset:49152
	ds_read_b128 v[234:237], v175 offset:2048
	ds_read_b128 v[238:241], v175 offset:4096
	ds_read_b128 v[242:245], v175 offset:6144
	ds_read_b128 v[136:139], v177 offset:0
	ds_read_b128 v[140:143], v177 offset:2048
	ds_read_b128 v[144:147], v177 offset:4096
	ds_read_b128 v[148:151], v177 offset:6144
	ds_read_b128 v[186:189], v176 offset:51200
	ds_read_b128 v[190:193], v176 offset:53248
	ds_read_b128 v[194:197], v176 offset:55296
	s_waitcnt lgkmcnt(10)
	v_mfma_f32_16x16x32_f16 v[124:127], v[230:233], v[182:185], v[124:127]
	s_waitcnt lgkmcnt(9)
	v_mfma_f32_16x16x32_f16 v[92:95], v[234:237], v[182:185], v[92:95]
	s_waitcnt lgkmcnt(8)
	v_mfma_f32_16x16x32_f16 v[60:63], v[238:241], v[182:185], v[60:63]
	s_waitcnt lgkmcnt(7)
	v_mfma_f32_16x16x32_f16 v[28:31], v[242:245], v[182:185], v[28:31]
	s_barrier
	ds_read_b128 v[198:201], v178 offset:49152
	ds_read_b128 v[202:205], v178 offset:51200
	ds_read_b128 v[222:225], v178 offset:53248
	ds_read_b128 v[226:229], v178 offset:55296
	s_waitcnt lgkmcnt(6)
	v_mfma_f32_16x16x32_f16 v[120:123], v[230:233], v[186:189], v[120:123]
	v_mfma_f32_16x16x32_f16 v[88:91], v[234:237], v[186:189], v[88:91]
	v_mfma_f32_16x16x32_f16 v[56:59], v[238:241], v[186:189], v[56:59]
	v_mfma_f32_16x16x32_f16 v[24:27], v[242:245], v[186:189], v[24:27]
	s_waitcnt lgkmcnt(5)
	v_mfma_f32_16x16x32_f16 v[116:119], v[230:233], v[190:193], v[116:119]
	v_mfma_f32_16x16x32_f16 v[84:87], v[234:237], v[190:193], v[84:87]
	v_mfma_f32_16x16x32_f16 v[52:55], v[238:241], v[190:193], v[52:55]
	v_mfma_f32_16x16x32_f16 v[20:23], v[242:245], v[190:193], v[20:23]
	s_waitcnt lgkmcnt(4)
	v_mfma_f32_16x16x32_f16 v[112:115], v[230:233], v[194:197], v[112:115]
	v_mfma_f32_16x16x32_f16 v[80:83], v[234:237], v[194:197], v[80:83]
	v_mfma_f32_16x16x32_f16 v[48:51], v[238:241], v[194:197], v[48:51]
	v_mfma_f32_16x16x32_f16 v[16:19], v[242:245], v[194:197], v[16:19]
	s_waitcnt lgkmcnt(3)
	v_mfma_f32_16x16x32_f16 v[124:127], v[136:139], v[198:201], v[124:127]
	v_mfma_f32_16x16x32_f16 v[92:95], v[140:143], v[198:201], v[92:95]
	v_mfma_f32_16x16x32_f16 v[60:63], v[144:147], v[198:201], v[60:63]
	v_mfma_f32_16x16x32_f16 v[28:31], v[148:151], v[198:201], v[28:31]
	s_waitcnt lgkmcnt(2)
	v_mfma_f32_16x16x32_f16 v[120:123], v[136:139], v[202:205], v[120:123]
	v_mfma_f32_16x16x32_f16 v[88:91], v[140:143], v[202:205], v[88:91]
	v_mfma_f32_16x16x32_f16 v[56:59], v[144:147], v[202:205], v[56:59]
	v_mfma_f32_16x16x32_f16 v[24:27], v[148:151], v[202:205], v[24:27]
	s_waitcnt lgkmcnt(1)
	v_mfma_f32_16x16x32_f16 v[116:119], v[136:139], v[222:225], v[116:119]
	v_mfma_f32_16x16x32_f16 v[84:87], v[140:143], v[222:225], v[84:87]
	v_mfma_f32_16x16x32_f16 v[52:55], v[144:147], v[222:225], v[52:55]
	v_mfma_f32_16x16x32_f16 v[20:23], v[148:151], v[222:225], v[20:23]
	s_waitcnt lgkmcnt(0)
	v_mfma_f32_16x16x32_f16 v[112:115], v[136:139], v[226:229], v[112:115]
	v_mfma_f32_16x16x32_f16 v[80:83], v[140:143], v[226:229], v[80:83]
	v_mfma_f32_16x16x32_f16 v[48:51], v[144:147], v[226:229], v[48:51]
	v_mfma_f32_16x16x32_f16 v[16:19], v[148:151], v[226:229], v[16:19]
	s_waitcnt vmcnt(0)
	s_barrier
	ds_read_b128 v[182:185], v176 offset:16384
	ds_read_b128 v[186:189], v176 offset:18432
	ds_read_b128 v[190:193], v176 offset:20480
	ds_read_b128 v[194:197], v176 offset:22528
	ds_read_b128 v[198:201], v178 offset:16384
	ds_read_b128 v[202:205], v178 offset:18432
	ds_read_b128 v[222:225], v178 offset:20480
	ds_read_b128 v[226:229], v178 offset:22528
	s_waitcnt lgkmcnt(7)
	v_mfma_f32_16x16x32_f16 v[108:111], v[230:233], v[182:185], v[108:111]
	v_mfma_f32_16x16x32_f16 v[76:79], v[234:237], v[182:185], v[76:79]
	v_mfma_f32_16x16x32_f16 v[44:47], v[238:241], v[182:185], v[44:47]
	v_mfma_f32_16x16x32_f16 v[12:15], v[242:245], v[182:185], v[12:15]
	s_waitcnt lgkmcnt(6)
	v_mfma_f32_16x16x32_f16 v[104:107], v[230:233], v[186:189], v[104:107]
	v_mfma_f32_16x16x32_f16 v[72:75], v[234:237], v[186:189], v[72:75]
	v_mfma_f32_16x16x32_f16 v[40:43], v[238:241], v[186:189], v[40:43]
	v_mfma_f32_16x16x32_f16 v[8:11], v[242:245], v[186:189], v[8:11]
	s_waitcnt lgkmcnt(5)
	v_mfma_f32_16x16x32_f16 v[100:103], v[230:233], v[190:193], v[100:103]
	v_mfma_f32_16x16x32_f16 v[68:71], v[234:237], v[190:193], v[68:71]
	v_mfma_f32_16x16x32_f16 v[36:39], v[238:241], v[190:193], v[36:39]
	v_mfma_f32_16x16x32_f16 v[4:7], v[242:245], v[190:193], v[4:7]
	s_waitcnt lgkmcnt(4)
	v_mfma_f32_16x16x32_f16 v[96:99], v[230:233], v[194:197], v[96:99]
	v_mfma_f32_16x16x32_f16 v[64:67], v[234:237], v[194:197], v[64:67]
	v_mfma_f32_16x16x32_f16 v[32:35], v[238:241], v[194:197], v[32:35]
	v_mfma_f32_16x16x32_f16 v[0:3], v[242:245], v[194:197], v[0:3]
	s_waitcnt lgkmcnt(3)
	v_mfma_f32_16x16x32_f16 v[108:111], v[136:139], v[198:201], v[108:111]
	v_mfma_f32_16x16x32_f16 v[76:79], v[140:143], v[198:201], v[76:79]
	v_mfma_f32_16x16x32_f16 v[44:47], v[144:147], v[198:201], v[44:47]
	v_mfma_f32_16x16x32_f16 v[12:15], v[148:151], v[198:201], v[12:15]
	s_waitcnt lgkmcnt(2)
	v_mfma_f32_16x16x32_f16 v[104:107], v[136:139], v[202:205], v[104:107]
	v_mfma_f32_16x16x32_f16 v[72:75], v[140:143], v[202:205], v[72:75]
	v_mfma_f32_16x16x32_f16 v[40:43], v[144:147], v[202:205], v[40:43]
	v_mfma_f32_16x16x32_f16 v[8:11], v[148:151], v[202:205], v[8:11]
	s_waitcnt lgkmcnt(1)
	v_mfma_f32_16x16x32_f16 v[100:103], v[136:139], v[222:225], v[100:103]
	v_mfma_f32_16x16x32_f16 v[68:71], v[140:143], v[222:225], v[68:71]
	v_mfma_f32_16x16x32_f16 v[36:39], v[144:147], v[222:225], v[36:39]
	v_mfma_f32_16x16x32_f16 v[4:7], v[148:151], v[222:225], v[4:7]
	s_waitcnt lgkmcnt(0)
	v_mfma_f32_16x16x32_f16 v[96:99], v[136:139], v[226:229], v[96:99]
	v_mfma_f32_16x16x32_f16 v[64:67], v[140:143], v[226:229], v[64:67]
	v_mfma_f32_16x16x32_f16 v[32:35], v[144:147], v[226:229], v[32:35]
	v_mfma_f32_16x16x32_f16 v[0:3], v[148:151], v[226:229], v[0:3]
	s_nop 7
	s_cmpk_lt_u32 s9, 0x620
	s_cbranch_scc0 .Lgin_cls_lat
	s_cmp_lt_u32 s16, 4
	s_cbranch_scc1 .Lgin_plain
	s_sub_u32 s4, s16, 8
	s_cmp_lt_u32 s4, 28
	s_cbranch_scc1 .Lgin_plain
	s_sub_u32 s4, s16, 45
	s_cmp_lt_u32 s4, 3
	s_cbranch_scc1 .Lgin_plain
	s_sub_u32 s4, s16, 4
	s_cmp_lt_u32 s4, 2
	s_cbranch_scc1 .Lgin_kvar
	s_sub_u32 s4, s16, 37
	s_cmp_lt_u32 s4, 3
	s_cbranch_scc1 .Lgin_kvar
	s_sub_u32 s4, s16, 6
	s_cmp_lt_u32 s4, 2
	s_cbranch_scc1 .Lgin_vvar
	s_sub_u32 s4, s16, 41
	s_cmp_lt_u32 s4, 3
	s_cbranch_scc1 .Lgin_vvar
	s_branch .Lgin_notplain
